# RG-LRU pass 3 carry scans: chunks of 8 LDS reads in flight instead of one read+wait per step
# speedup vs baseline: 1.0387x; 1.0039x over previous
.Lcs_b8:
	s_sub_u32 s98, s12, s37
	s_cmp_lt_u32 s98, 8
	s_cbranch_scc1 .Lcs_b1
	v_add_u32_e32 v13, 0xfffff200, v9
	ds_read_b64 v[216:217], v13 offset:3584
	ds_read_b64 v[218:219], v13 offset:3072
	ds_read_b64 v[220:221], v13 offset:2560
	ds_read_b64 v[222:223], v13 offset:2048
	ds_read_b64 v[224:225], v13 offset:1536
	ds_read_b64 v[226:227], v13 offset:1024
	ds_read_b64 v[228:229], v13 offset:512
	ds_read_b64 v[230:231], v13
	s_add_i32 s12, s12, -8
	v_add_u32_e32 v9, 0xfffff000, v9
	s_waitcnt lgkmcnt(7)
	v_fmac_f32_e32 v217, v8, v216
	s_waitcnt lgkmcnt(6)
	v_fmac_f32_e32 v219, v217, v218
	s_waitcnt lgkmcnt(5)
	v_fmac_f32_e32 v221, v219, v220
	s_waitcnt lgkmcnt(4)
	v_fmac_f32_e32 v223, v221, v222
	s_waitcnt lgkmcnt(3)
	v_fmac_f32_e32 v225, v223, v224
	s_waitcnt lgkmcnt(2)
	v_fmac_f32_e32 v227, v225, v226
	s_waitcnt lgkmcnt(1)
	v_fmac_f32_e32 v229, v227, v228
	s_waitcnt lgkmcnt(0)
	v_fmac_f32_e32 v231, v229, v230
	v_mov_b32_e32 v8, v231
	s_branch .Lcs_b8
.Lcs_b1:
	s_cmp_gt_u32 s12, s37
	s_cbranch_scc0 .LBB0_349

.Lcs_f8:
	s_cmp_lt_u32 s2, 8
	s_cbranch_scc1 .Lcs_f1
	ds_read_b64 v[216:217], v9
	ds_read_b64 v[218:219], v9 offset:512
	ds_read_b64 v[220:221], v9 offset:1024
	ds_read_b64 v[222:223], v9 offset:1536
	ds_read_b64 v[224:225], v9 offset:2048
	ds_read_b64 v[226:227], v9 offset:2560
	ds_read_b64 v[228:229], v9 offset:3072
	ds_read_b64 v[230:231], v9 offset:3584
	s_add_i32 s2, s2, -8
	v_add_u32_e32 v9, 0x1000, v9
	s_waitcnt lgkmcnt(7)
	v_fmac_f32_e32 v217, v8, v216
	s_waitcnt lgkmcnt(6)
	v_fmac_f32_e32 v219, v217, v218
	s_waitcnt lgkmcnt(5)
	v_fmac_f32_e32 v221, v219, v220
	s_waitcnt lgkmcnt(4)
	v_fmac_f32_e32 v223, v221, v222
	s_waitcnt lgkmcnt(3)
	v_fmac_f32_e32 v225, v223, v224
	s_waitcnt lgkmcnt(2)
	v_fmac_f32_e32 v227, v225, v226
	s_waitcnt lgkmcnt(1)
	v_fmac_f32_e32 v229, v227, v228
	s_waitcnt lgkmcnt(0)
	v_fmac_f32_e32 v231, v229, v230
	v_mov_b32_e32 v8, v231
	s_branch .Lcs_f8
.Lcs_f1:
	s_cmp_eq_u32 s2, 0
	s_cbranch_scc1 .LBB0_354
